# merge-GEMM hook: the last three gate loads of the second half issued before the wait (one round trip fewer per hook)
# baseline (speedup 1.0000x reference)
; #define PG8_STAGE(bufoff, gbase, voff) do { _Pragma("unroll") for (int _i = 0; _i < 2; ++_i) \
;         __builtin_amdgcn_global_load_lds((const unsigned*)((const char*)(gbase) + (voff)[_i]), (LAS unsigned*)(lds + (bufoff) + ldsw + _i * 8192), 16, 0, 0); } while (0)
; #define PG8_LDA(dst, b, h) do { _Pragma("unroll") for (int m = 0; m < 4; ++m) _Pragma("unroll") for (int k = 0; k < 2; ++k) dst[m][k] = *(const LAS bf16x8*)(lds + PG8_SA(b, h) + aoff + m * 2048 + k * 1024); } while (0)
; #define PG8_WAIT_V(n) asm volatile("s_waitcnt vmcnt(" #n ")" ::: "memory")
; #define PG8_WAIT_L(n) asm volatile("s_waitcnt lgkmcnt(" #n ")" ::: "memory")
; template <class Epi, class Sched>
; __device__ __forceinline__ void gemm_phase(LAS unsigned char* lds, const Gemm g, const Sched& S, const Epi& E) {
;     ...
;         for (int t = 0; t < nt; t += 2) {
;             const bool last = (t == nt - 2);
;             const char* a1 = cA + (size_t)(t + 1) * kstep;
;             const char* a2 = last ? nA : cA + (size_t)(t + 2) * kstep; const char* b2 = last ? nB : cB + (size_t)(t + 2) * kstep;
;             const char* a3 = a2 + kstep; const char* b3 = b2 + kstep;
;             PG8_LDB(B0, 0, 0); PG8_SCHED; PG8_LDA(At, 0, 0); PG8_STAGE(PG8_SA(1, 1), a1 + hstepA, voffA);
;             PG8_WAIT_L(8); PG8_BAR; PG8_WAIT_L(0); PG8_MMA(0, 0, At, B0); PG8_BAR; PG8_SCHED;
;             PG8_LDB(B1, 0, 1); PG8_STAGE(PG8_SB(0, 0), b2, voffB);
;             PG8_BAR; PG8_WAIT_L(0); PG8_MMA(0, 1, At, B1); PG8_BAR;
;             PG8_LDA(At, 0, 1); PG8_STAGE(PG8_SA(0, 0), a2, voffA);
;             PG8_BAR; PG8_WAIT_L(0); PG8_MMA(1, 0, At, B0); PG8_BAR; PG8_SCHED;
;             PG8_STAGE(PG8_SB(0, 1), b2 + hstepB, voffB);
;             PG8_WAIT_V(6); PG8_BAR; PG8_MMA(1, 1, At, B1); PG8_BAR;
;             PG8_LDB(B0, 1, 0); PG8_SCHED; PG8_LDA(At, 1, 0); PG8_STAGE(PG8_SA(0, 1), a2 + hstepA, voffA);
;             PG8_WAIT_L(8); PG8_BAR; PG8_WAIT_L(0); PG8_MMA(0, 0, At, B0); PG8_BAR; PG8_SCHED;
;             PG8_LDB(B1, 1, 1); PG8_STAGE(PG8_SB(1, 0), b3, voffB);
;             PG8_BAR; PG8_WAIT_L(0); PG8_MMA(0, 1, At, B1); PG8_BAR;
;             PG8_LDA(At, 1, 1); PG8_STAGE(PG8_SA(1, 0), a3, voffA);
;             PG8_BAR; PG8_WAIT_L(0); PG8_MMA(1, 0, At, B0); PG8_BAR; PG8_SCHED;
;             PG8_STAGE(PG8_SB(1, 1), b3 + hstepB, voffB);
;             PG8_WAIT_V(6); PG8_BAR; PG8_MMA(1, 1, At, B1); PG8_BAR;
.LBB0_45:
	s_add_i32 s58, s58, 2
	s_add_u32 s22, s18, 0xfffc0080
	s_addc_u32 s23, s19, -1
	s_add_i32 s60, 0, 0x10000
	v_add_u32_e32 v1, s60, v178
	ds_read_b128 v[144:147], v1
	ds_read_b128 v[148:151], v1 offset:1024
	ds_read_b128 v[152:155], v1 offset:2048
	ds_read_b128 v[156:159], v1 offset:3072
	s_cmpk_eq_i32 s59, 0xe00
	s_cselect_b64 s[2:3], -1, 0
	s_and_b64 s[20:21], s[2:3], exec
	s_cselect_b32 s23, s0, s23
	s_cselect_b32 s22, s1, s22
	s_cselect_b32 s21, s46, s49
	s_cselect_b32 s20, s47, s48
	v_lshl_add_u64 v[2:3], s[18:19], 0, v[142:143]
	s_add_i32 m0, s38, 0xc000
	ds_read_b128 v[160:163], v179
	ds_read_b128 v[164:167], v179 offset:1024
	ds_read_b128 v[168:171], v179 offset:2048
	ds_read_b128 v[172:175], v179 offset:3072
	ds_read_b128 v[180:183], v179 offset:4096
	ds_read_b128 v[184:187], v179 offset:5120
	ds_read_b128 v[190:193], v179 offset:6144
	ds_read_b128 v[194:197], v179 offset:7168
	global_load_lds_dwordx4 v[2:3], off
	v_lshl_add_u64 v[2:3], s[18:19], 0, v[140:141]
	s_add_i32 m0, s38, 0xe000
	s_nop 0
	global_load_lds_dwordx4 v[2:3], off
	s_waitcnt lgkmcnt(8)
	s_barrier
	s_waitcnt lgkmcnt(0)
	s_setprio 1
	s_waitcnt lgkmcnt(0)
	v_mfma_f32_16x16x32_bf16 v[128:131], v[144:147], v[160:163], v[128:131]
	v_mfma_f32_16x16x32_bf16 v[124:127], v[152:155], v[160:163], v[124:127]
	v_mfma_f32_16x16x32_bf16 v[112:115], v[144:147], v[168:171], v[112:115]
	v_mfma_f32_16x16x32_bf16 v[108:111], v[152:155], v[168:171], v[108:111]
	v_mfma_f32_16x16x32_bf16 v[96:99], v[144:147], v[180:183], v[96:99]
	v_mfma_f32_16x16x32_bf16 v[92:95], v[152:155], v[180:183], v[92:95]
	v_mfma_f32_16x16x32_bf16 v[80:83], v[144:147], v[190:193], v[80:83]
	v_mfma_f32_16x16x32_bf16 v[76:79], v[152:155], v[190:193], v[76:79]
	v_mfma_f32_16x16x32_bf16 v[128:131], v[148:151], v[164:167], v[128:131]
	v_mfma_f32_16x16x32_bf16 v[124:127], v[156:159], v[164:167], v[124:127]
	v_mfma_f32_16x16x32_bf16 v[112:115], v[148:151], v[172:175], v[112:115]
	v_mfma_f32_16x16x32_bf16 v[108:111], v[156:159], v[172:175], v[108:111]
	v_mfma_f32_16x16x32_bf16 v[96:99], v[148:151], v[184:187], v[96:99]
	v_mfma_f32_16x16x32_bf16 v[92:95], v[156:159], v[184:187], v[92:95]
	v_mfma_f32_16x16x32_bf16 v[80:83], v[148:151], v[194:197], v[80:83]
	v_mfma_f32_16x16x32_bf16 v[76:79], v[156:159], v[194:197], v[76:79]
	s_setprio 0
	s_barrier
	s_add_i32 s62, 0, 0x14000
	s_add_i32 s60, s60, s34
	v_add_u32_e32 v1, s62, v178
	v_lshl_add_u64 v[176:177], s[20:21], 0, v[136:137]
	s_mov_b32 m0, s60
	ds_read_b128 v[200:203], v1
	ds_read_b128 v[204:207], v1 offset:1024
	ds_read_b128 v[208:211], v1 offset:2048
	ds_read_b128 v[212:215], v1 offset:3072
	global_load_lds_dwordx4 v[176:177], off
	v_lshl_add_u64 v[198:199], s[20:21], 0, v[132:133]
	s_add_i32 m0, s60, 0x2000
	s_nop 0
	global_load_lds_dwordx4 v[198:199], off
	s_barrier
	s_waitcnt lgkmcnt(0)
	s_setprio 1
	s_waitcnt lgkmcnt(0)
	v_mfma_f32_16x16x32_bf16 v[120:123], v[200:203], v[160:163], v[120:123]
	v_mfma_f32_16x16x32_bf16 v[116:119], v[208:211], v[160:163], v[116:119]
	v_mfma_f32_16x16x32_bf16 v[104:107], v[200:203], v[168:171], v[104:107]
	v_mfma_f32_16x16x32_bf16 v[100:103], v[208:211], v[168:171], v[100:103]
	v_mfma_f32_16x16x32_bf16 v[88:91], v[200:203], v[180:183], v[88:91]
	v_mfma_f32_16x16x32_bf16 v[84:87], v[208:211], v[180:183], v[84:87]
	v_mfma_f32_16x16x32_bf16 v[72:75], v[200:203], v[190:193], v[72:75]
	v_mfma_f32_16x16x32_bf16 v[68:71], v[208:211], v[190:193], v[68:71]
	v_mfma_f32_16x16x32_bf16 v[120:123], v[204:207], v[164:167], v[120:123]
	v_mfma_f32_16x16x32_bf16 v[116:119], v[212:215], v[164:167], v[116:119]
	v_mfma_f32_16x16x32_bf16 v[104:107], v[204:207], v[172:175], v[104:107]
	v_mfma_f32_16x16x32_bf16 v[100:103], v[212:215], v[172:175], v[100:103]
	v_mfma_f32_16x16x32_bf16 v[88:91], v[204:207], v[184:187], v[88:91]
	v_mfma_f32_16x16x32_bf16 v[84:87], v[212:215], v[184:187], v[84:87]
	v_mfma_f32_16x16x32_bf16 v[72:75], v[204:207], v[194:197], v[72:75]
	v_mfma_f32_16x16x32_bf16 v[68:71], v[212:215], v[194:197], v[68:71]
	s_setprio 0
	s_mov_b32 m0, s38
	v_lshl_add_u64 v[216:217], s[22:23], 0, v[138:139]
	s_barrier
	ds_read_b128 v[160:163], v179 offset:16384
	ds_read_b128 v[164:167], v179 offset:17408
	ds_read_b128 v[168:171], v179 offset:18432
	ds_read_b128 v[172:175], v179 offset:19456
	ds_read_b128 v[180:183], v179 offset:20480
	ds_read_b128 v[184:187], v179 offset:21504
	ds_read_b128 v[190:193], v179 offset:22528
	ds_read_b128 v[194:197], v179 offset:23552
	global_load_lds_dwordx4 v[216:217], off
	v_lshl_add_u64 v[218:219], s[22:23], 0, v[134:135]
	s_mov_b32 m0, s39
	s_nop 0
	global_load_lds_dwordx4 v[218:219], off
	s_barrier
	s_waitcnt lgkmcnt(0)
	s_setprio 1
	s_waitcnt lgkmcnt(0)
	v_mfma_f32_16x16x32_bf16 v[64:67], v[144:147], v[160:163], v[64:67]
	v_mfma_f32_16x16x32_bf16 v[60:63], v[152:155], v[160:163], v[60:63]
	v_mfma_f32_16x16x32_bf16 v[48:51], v[144:147], v[168:171], v[48:51]
	v_mfma_f32_16x16x32_bf16 v[44:47], v[152:155], v[168:171], v[44:47]
	v_mfma_f32_16x16x32_bf16 v[32:35], v[144:147], v[180:183], v[32:35]
	v_mfma_f32_16x16x32_bf16 v[28:31], v[152:155], v[180:183], v[28:31]
	v_mfma_f32_16x16x32_bf16 v[16:19], v[144:147], v[190:193], v[16:19]
	v_mfma_f32_16x16x32_bf16 v[12:15], v[152:155], v[190:193], v[12:15]
	v_mfma_f32_16x16x32_bf16 v[64:67], v[148:151], v[164:167], v[64:67]
	v_mfma_f32_16x16x32_bf16 v[60:63], v[156:159], v[164:167], v[60:63]
	v_mfma_f32_16x16x32_bf16 v[48:51], v[148:151], v[172:175], v[48:51]
	v_mfma_f32_16x16x32_bf16 v[44:47], v[156:159], v[172:175], v[44:47]
	v_mfma_f32_16x16x32_bf16 v[32:35], v[148:151], v[184:187], v[32:35]
	v_mfma_f32_16x16x32_bf16 v[28:31], v[156:159], v[184:187], v[28:31]
	v_mfma_f32_16x16x32_bf16 v[16:19], v[148:151], v[194:197], v[16:19]
	v_mfma_f32_16x16x32_bf16 v[12:15], v[156:159], v[194:197], v[12:15]
	s_setprio 0
	s_barrier
; #define PG8_STAGE(bufoff, gbase, voff) do { _Pragma("unroll") for (int _i = 0; _i < 2; ++_i) \
;         __builtin_amdgcn_global_load_lds((const unsigned*)((const char*)(gbase) + (voff)[_i]), (LAS unsigned*)(lds + (bufoff) + ldsw + _i * 8192), 16, 0, 0); } while (0)
; #define PG8_LDA(dst, b, h) do { _Pragma("unroll") for (int m = 0; m < 4; ++m) _Pragma("unroll") for (int k = 0; k < 2; ++k) dst[m][k] = *(const LAS bf16x8*)(lds + PG8_SA(b, h) + aoff + m * 2048 + k * 1024); } while (0)
; #define PG8_WAIT_V(n) asm volatile("s_waitcnt vmcnt(" #n ")" ::: "memory")
; #define PG8_WAIT_L(n) asm volatile("s_waitcnt lgkmcnt(" #n ")" ::: "memory")
; template <class Epi, class Sched>
; __device__ __forceinline__ void gemm_phase(LAS unsigned char* lds, const Gemm g, const Sched& S, const Epi& E) {
;     ...
;         for (int t = 0; t < nt; t += 2) {
;             const bool last = (t == nt - 2);
;             const char* a1 = cA + (size_t)(t + 1) * kstep;
;             const char* a2 = last ? nA : cA + (size_t)(t + 2) * kstep; const char* b2 = last ? nB : cB + (size_t)(t + 2) * kstep;
;             const char* a3 = a2 + kstep; const char* b3 = b2 + kstep;
;             PG8_LDB(B0, 0, 0); PG8_SCHED; PG8_LDA(At, 0, 0); PG8_STAGE(PG8_SA(1, 1), a1 + hstepA, voffA);
;             PG8_WAIT_L(8); PG8_BAR; PG8_WAIT_L(0); PG8_MMA(0, 0, At, B0); PG8_BAR; PG8_SCHED;
;             PG8_LDB(B1, 0, 1); PG8_STAGE(PG8_SB(0, 0), b2, voffB);
;             PG8_BAR; PG8_WAIT_L(0); PG8_MMA(0, 1, At, B1); PG8_BAR;
;             PG8_LDA(At, 0, 1); PG8_STAGE(PG8_SA(0, 0), a2, voffA);
;             PG8_BAR; PG8_WAIT_L(0); PG8_MMA(1, 0, At, B0); PG8_BAR; PG8_SCHED;
;             PG8_STAGE(PG8_SB(0, 1), b2 + hstepB, voffB);
;             PG8_WAIT_V(6); PG8_BAR; PG8_MMA(1, 1, At, B1); PG8_BAR;
;             PG8_LDB(B0, 1, 0); PG8_SCHED; PG8_LDA(At, 1, 0); PG8_STAGE(PG8_SA(0, 1), a2 + hstepA, voffA);
;             PG8_WAIT_L(8); PG8_BAR; PG8_WAIT_L(0); PG8_MMA(0, 0, At, B0); PG8_BAR; PG8_SCHED;
;             PG8_LDB(B1, 1, 1); PG8_STAGE(PG8_SB(1, 0), b3, voffB);
;             PG8_BAR; PG8_WAIT_L(0); PG8_MMA(0, 1, At, B1); PG8_BAR;
;             PG8_LDA(At, 1, 1); PG8_STAGE(PG8_SA(1, 0), a3, voffA);
;             PG8_BAR; PG8_WAIT_L(0); PG8_MMA(1, 0, At, B0); PG8_BAR; PG8_SCHED;
;             PG8_STAGE(PG8_SB(1, 1), b3 + hstepB, voffB);
;             PG8_WAIT_V(6); PG8_BAR; PG8_MMA(1, 1, At, B1); PG8_BAR;
	s_add_u32 s60, s20, 0x40000
	s_addc_u32 s61, s21, 0
	s_add_i32 s62, s62, s34
	v_lshl_add_u64 v[2:3], s[60:61], 0, v[136:137]
	s_mov_b32 m0, s62
	s_nop 0
	global_load_lds_dwordx4 v[2:3], off
	v_lshl_add_u64 v[2:3], s[60:61], 0, v[132:133]
	s_add_i32 m0, s62, 0x2000
	s_nop 0
	global_load_lds_dwordx4 v[2:3], off
	s_waitcnt vmcnt(6)
	s_barrier
	s_setprio 1
	v_mfma_f32_16x16x32_bf16 v[56:59], v[200:203], v[160:163], v[56:59]
	v_mfma_f32_16x16x32_bf16 v[52:55], v[208:211], v[160:163], v[52:55]
	v_mfma_f32_16x16x32_bf16 v[40:43], v[200:203], v[168:171], v[40:43]
	v_mfma_f32_16x16x32_bf16 v[36:39], v[208:211], v[168:171], v[36:39]
	v_mfma_f32_16x16x32_bf16 v[24:27], v[200:203], v[180:183], v[24:27]
	v_mfma_f32_16x16x32_bf16 v[20:23], v[208:211], v[180:183], v[20:23]
	v_mfma_f32_16x16x32_bf16 v[8:11], v[200:203], v[190:193], v[8:11]
	v_mfma_f32_16x16x32_bf16 v[2:5], v[208:211], v[190:193], v[4:7]
	v_mfma_f32_16x16x32_bf16 v[56:59], v[204:207], v[164:167], v[56:59]
	v_mfma_f32_16x16x32_bf16 v[52:55], v[212:215], v[164:167], v[52:55]
	v_mfma_f32_16x16x32_bf16 v[40:43], v[204:207], v[172:175], v[40:43]
	v_mfma_f32_16x16x32_bf16 v[36:39], v[212:215], v[172:175], v[36:39]
	v_mfma_f32_16x16x32_bf16 v[24:27], v[204:207], v[184:187], v[24:27]
	v_mfma_f32_16x16x32_bf16 v[20:23], v[212:215], v[184:187], v[20:23]
	v_mfma_f32_16x16x32_bf16 v[8:11], v[204:207], v[194:197], v[8:11]
	v_mfma_f32_16x16x32_bf16 v[2:5], v[212:215], v[194:197], v[2:5]
	s_setprio 0
	s_add_i32 s60, 0, 0x18000
	v_add_u32_e32 v1, s60, v178
	s_barrier
	ds_read_b128 v[144:147], v1
	ds_read_b128 v[148:151], v1 offset:1024
	ds_read_b128 v[152:155], v1 offset:2048
	ds_read_b128 v[156:159], v1 offset:3072
	s_add_u32 s22, s22, 0x40000
	s_addc_u32 s23, s23, 0
	s_mov_b32 m0, s40
	v_lshl_add_u64 v[6:7], s[22:23], 0, v[138:139]
	ds_read_b128 v[160:163], v179 offset:32768
	ds_read_b128 v[164:167], v179 offset:33792
	ds_read_b128 v[168:171], v179 offset:34816
	ds_read_b128 v[172:175], v179 offset:35840
	ds_read_b128 v[180:183], v179 offset:36864
	ds_read_b128 v[184:187], v179 offset:37888
	ds_read_b128 v[190:193], v179 offset:38912
	ds_read_b128 v[194:197], v179 offset:39936
	global_load_lds_dwordx4 v[6:7], off
	v_lshl_add_u64 v[6:7], s[22:23], 0, v[134:135]
	s_mov_b32 m0, s41
	s_nop 0
	global_load_lds_dwordx4 v[6:7], off
	s_waitcnt lgkmcnt(8)
	s_barrier
	s_waitcnt lgkmcnt(0)
	s_setprio 1
	s_waitcnt lgkmcnt(0)
	v_mfma_f32_16x16x32_bf16 v[128:131], v[144:147], v[160:163], v[128:131]
	v_mfma_f32_16x16x32_bf16 v[124:127], v[152:155], v[160:163], v[124:127]
	v_mfma_f32_16x16x32_bf16 v[112:115], v[144:147], v[168:171], v[112:115]
	v_mfma_f32_16x16x32_bf16 v[108:111], v[152:155], v[168:171], v[108:111]
	v_mfma_f32_16x16x32_bf16 v[96:99], v[144:147], v[180:183], v[96:99]
	v_mfma_f32_16x16x32_bf16 v[92:95], v[152:155], v[180:183], v[92:95]
	v_mfma_f32_16x16x32_bf16 v[80:83], v[144:147], v[190:193], v[80:83]
	v_mfma_f32_16x16x32_bf16 v[76:79], v[152:155], v[190:193], v[76:79]
	v_mfma_f32_16x16x32_bf16 v[128:131], v[148:151], v[164:167], v[128:131]
	v_mfma_f32_16x16x32_bf16 v[124:127], v[156:159], v[164:167], v[124:127]
	v_mfma_f32_16x16x32_bf16 v[112:115], v[148:151], v[172:175], v[112:115]
	v_mfma_f32_16x16x32_bf16 v[108:111], v[156:159], v[172:175], v[108:111]
	v_mfma_f32_16x16x32_bf16 v[96:99], v[148:151], v[184:187], v[96:99]
	v_mfma_f32_16x16x32_bf16 v[92:95], v[156:159], v[184:187], v[92:95]
	v_mfma_f32_16x16x32_bf16 v[80:83], v[148:151], v[194:197], v[80:83]
	v_mfma_f32_16x16x32_bf16 v[76:79], v[156:159], v[194:197], v[76:79]
	s_setprio 0
	s_barrier
	s_add_i32 s22, 0, 0x1c000
	s_add_i32 s23, s60, s34
	v_add_u32_e32 v1, s22, v178
	v_lshl_add_u64 v[6:7], v[176:177], 0, s[90:91]
	s_mov_b32 m0, s23
	ds_read_b128 v[200:203], v1
	ds_read_b128 v[204:207], v1 offset:1024
	ds_read_b128 v[208:211], v1 offset:2048
	ds_read_b128 v[212:215], v1 offset:3072
	global_load_lds_dwordx4 v[6:7], off
	v_lshl_add_u64 v[6:7], v[198:199], 0, s[90:91]
	s_add_i32 m0, s23, 0x2000
	s_nop 0
	global_load_lds_dwordx4 v[6:7], off
	s_barrier
	s_waitcnt lgkmcnt(0)
	s_setprio 1
	s_waitcnt lgkmcnt(0)
	v_mfma_f32_16x16x32_bf16 v[120:123], v[200:203], v[160:163], v[120:123]
	v_mfma_f32_16x16x32_bf16 v[116:119], v[208:211], v[160:163], v[116:119]
	v_mfma_f32_16x16x32_bf16 v[104:107], v[200:203], v[168:171], v[104:107]
	v_mfma_f32_16x16x32_bf16 v[100:103], v[208:211], v[168:171], v[100:103]
	v_mfma_f32_16x16x32_bf16 v[88:91], v[200:203], v[180:183], v[88:91]
	v_mfma_f32_16x16x32_bf16 v[84:87], v[208:211], v[180:183], v[84:87]
	v_mfma_f32_16x16x32_bf16 v[72:75], v[200:203], v[190:193], v[72:75]
	v_mfma_f32_16x16x32_bf16 v[68:71], v[208:211], v[190:193], v[68:71]
	v_mfma_f32_16x16x32_bf16 v[120:123], v[204:207], v[164:167], v[120:123]
	v_mfma_f32_16x16x32_bf16 v[116:119], v[212:215], v[164:167], v[116:119]
	v_mfma_f32_16x16x32_bf16 v[104:107], v[204:207], v[172:175], v[104:107]
	v_mfma_f32_16x16x32_bf16 v[100:103], v[212:215], v[172:175], v[100:103]
	v_mfma_f32_16x16x32_bf16 v[88:91], v[204:207], v[184:187], v[88:91]
	v_mfma_f32_16x16x32_bf16 v[84:87], v[212:215], v[184:187], v[84:87]
	v_mfma_f32_16x16x32_bf16 v[72:75], v[204:207], v[194:197], v[72:75]
	v_mfma_f32_16x16x32_bf16 v[68:71], v[212:215], v[194:197], v[68:71]
	s_setprio 0
	s_mov_b32 m0, s42
	v_lshl_add_u64 v[6:7], v[216:217], 0, s[90:91]
	s_barrier
	ds_read_b128 v[160:163], v179 offset:49152
	ds_read_b128 v[164:167], v179 offset:50176
	ds_read_b128 v[168:171], v179 offset:51200
	ds_read_b128 v[172:175], v179 offset:52224
	ds_read_b128 v[180:183], v179 offset:53248
	ds_read_b128 v[184:187], v179 offset:54272
	ds_read_b128 v[190:193], v179 offset:55296
	ds_read_b128 v[194:197], v179 offset:56320
	global_load_lds_dwordx4 v[6:7], off
	v_lshl_add_u64 v[6:7], v[218:219], 0, s[90:91]
	s_mov_b32 m0, s43
	s_nop 0
	global_load_lds_dwordx4 v[6:7], off
	s_barrier
; __device__ __forceinline__ int opaque_tid() { int t = threadIdx.x; asm volatile("" : "+v"(t)); return t; }
; #define PG8_STAGE(bufoff, gbase, voff) do { _Pragma("unroll") for (int _i = 0; _i < 2; ++_i) \
;         __builtin_amdgcn_global_load_lds((const unsigned*)((const char*)(gbase) + (voff)[_i]), (LAS unsigned*)(lds + (bufoff) + ldsw + _i * 8192), 16, 0, 0); } while (0)
; #define PG8_LDA(dst, b, h) do { _Pragma("unroll") for (int m = 0; m < 4; ++m) _Pragma("unroll") for (int k = 0; k < 2; ++k) dst[m][k] = *(const LAS bf16x8*)(lds + PG8_SA(b, h) + aoff + m * 2048 + k * 1024); } while (0)
; #define PG8_BAR __builtin_amdgcn_s_barrier()
; template <class Epi, class Sched>
; __device__ __forceinline__ void gemm_phase(LAS unsigned char* lds, const Gemm g, const Sched& S, const Epi& E) {
;     ...
;             PG8_WAIT_V(6); PG8_BAR; PG8_MMA(1, 1, At, B1); PG8_BAR;
;             PG8_LDB(B0, 1, 0); PG8_SCHED; PG8_LDA(At, 1, 0); PG8_STAGE(PG8_SA(0, 1), a2 + hstepA, voffA);
;             PG8_WAIT_L(8); PG8_BAR; PG8_WAIT_L(0); PG8_MMA(0, 0, At, B0); PG8_BAR; PG8_SCHED;
;             PG8_LDB(B1, 1, 1); PG8_STAGE(PG8_SB(1, 0), b3, voffB);
;             PG8_BAR; PG8_WAIT_L(0); PG8_MMA(0, 1, At, B1); PG8_BAR;
;             PG8_LDA(At, 1, 1); PG8_STAGE(PG8_SA(1, 0), a3, voffA);
;             PG8_BAR; PG8_WAIT_L(0); PG8_MMA(1, 0, At, B0); PG8_BAR; PG8_SCHED;
;             PG8_STAGE(PG8_SB(1, 1), b3 + hstepB, voffB);
;             PG8_WAIT_V(6); PG8_BAR; PG8_MMA(1, 1, At, B1); PG8_BAR;
;             if constexpr (Epi::HOOK) { if ((((t + 2) & 3) == 0) && !last) E.hook(acc, cur, (t + 2) >> 2, wr, wc, fr, fq); }
;     __device__ __forceinline__ void hook(f32x4 (&acc)[2][2][4][2], const Unit& u, int nb, int wr, int wc, int fr, int fq) const {
;         { const int t_ = opaque_tid(); wr = t_ >> 8; wc = (t_ >> 6) & 3; fr = t_ & 15; fq = (t_ >> 4) & 3; }
;         const int row0 = u.pm * 256 + wr * 64 + fr, c0 = u.pn * 256 + wc * 32 + 8 * fq;
; #pragma unroll
;         for (int ai = 0; ai < 2; ++ai) {
;             u32x2 ga[4][2], gb[4][2];
; #pragma unroll
;             for (int m = 0; m < 4; ++m)
; #pragma unroll
;                 for (int bj = 0; bj < 2; ++bj) { const int row = row0 + ai * 128 + m * 16, c = c0 + bj * 128;
;                     ga[m][bj] = *(const u32x2*)(G8 + g8_off(row, (nb - 1) * 1024 + c)); gb[m][bj] = *(const u32x2*)(G8 + g8_off(row, nb * 1024 + c)); }
	s_waitcnt lgkmcnt(0)
	s_setprio 1
	s_waitcnt lgkmcnt(0)
	v_mfma_f32_16x16x32_bf16 v[64:67], v[144:147], v[160:163], v[64:67]
	v_mfma_f32_16x16x32_bf16 v[60:63], v[152:155], v[160:163], v[60:63]
	v_mfma_f32_16x16x32_bf16 v[48:51], v[144:147], v[168:171], v[48:51]
	v_mfma_f32_16x16x32_bf16 v[44:47], v[152:155], v[168:171], v[44:47]
	v_mfma_f32_16x16x32_bf16 v[32:35], v[144:147], v[180:183], v[32:35]
	v_mfma_f32_16x16x32_bf16 v[28:31], v[152:155], v[180:183], v[28:31]
	v_mfma_f32_16x16x32_bf16 v[16:19], v[144:147], v[190:193], v[16:19]
	v_mfma_f32_16x16x32_bf16 v[12:15], v[152:155], v[190:193], v[12:15]
	v_mfma_f32_16x16x32_bf16 v[64:67], v[148:151], v[164:167], v[64:67]
	v_mfma_f32_16x16x32_bf16 v[60:63], v[156:159], v[164:167], v[60:63]
	v_mfma_f32_16x16x32_bf16 v[48:51], v[148:151], v[172:175], v[48:51]
	v_mfma_f32_16x16x32_bf16 v[44:47], v[156:159], v[172:175], v[44:47]
	v_mfma_f32_16x16x32_bf16 v[32:35], v[148:151], v[184:187], v[32:35]
	v_mfma_f32_16x16x32_bf16 v[28:31], v[156:159], v[184:187], v[28:31]
	v_mfma_f32_16x16x32_bf16 v[16:19], v[148:151], v[194:197], v[16:19]
	v_mfma_f32_16x16x32_bf16 v[12:15], v[156:159], v[194:197], v[12:15]
	s_setprio 0
	s_barrier
	s_add_u32 s20, s20, 0x40080
	s_addc_u32 s21, s21, 0
	s_add_i32 s22, s22, s34
	v_lshl_add_u64 v[6:7], s[20:21], 0, v[136:137]
	s_mov_b32 m0, s22
	s_nop 0
	global_load_lds_dwordx4 v[6:7], off
	v_lshl_add_u64 v[6:7], s[20:21], 0, v[132:133]
	s_add_i32 m0, s22, 0x2000
	s_nop 0
	global_load_lds_dwordx4 v[6:7], off
	s_waitcnt vmcnt(6)
	s_barrier
	s_setprio 1
	v_mfma_f32_16x16x32_bf16 v[56:59], v[200:203], v[160:163], v[56:59]
	v_mfma_f32_16x16x32_bf16 v[52:55], v[208:211], v[160:163], v[52:55]
	v_mfma_f32_16x16x32_bf16 v[40:43], v[200:203], v[168:171], v[40:43]
	v_mfma_f32_16x16x32_bf16 v[36:39], v[208:211], v[168:171], v[36:39]
	v_mfma_f32_16x16x32_bf16 v[24:27], v[200:203], v[180:183], v[24:27]
	v_mfma_f32_16x16x32_bf16 v[20:23], v[208:211], v[180:183], v[20:23]
	v_mfma_f32_16x16x32_bf16 v[6:9], v[200:203], v[190:193], v[8:11]
	v_mfma_f32_16x16x32_bf16 v[2:5], v[208:211], v[190:193], v[2:5]
	v_mfma_f32_16x16x32_bf16 v[56:59], v[204:207], v[164:167], v[56:59]
	v_mfma_f32_16x16x32_bf16 v[52:55], v[212:215], v[164:167], v[52:55]
	v_mfma_f32_16x16x32_bf16 v[40:43], v[204:207], v[172:175], v[40:43]
	v_mfma_f32_16x16x32_bf16 v[36:39], v[212:215], v[172:175], v[36:39]
	v_mfma_f32_16x16x32_bf16 v[24:27], v[204:207], v[184:187], v[24:27]
	v_mfma_f32_16x16x32_bf16 v[20:23], v[212:215], v[184:187], v[20:23]
	v_mfma_f32_16x16x32_bf16 v[8:11], v[204:207], v[194:197], v[6:9]
	v_mfma_f32_16x16x32_bf16 v[4:7], v[212:215], v[194:197], v[2:5]
	s_setprio 0
	s_bitcmp0_b32 s58, 1
	s_cselect_b64 s[20:21], -1, 0
	s_or_b64 s[2:3], s[2:3], s[20:21]
	s_and_b64 vcc, exec, s[2:3]
	s_barrier
	s_cbranch_vccnz .LBB0_44
	v_mov_b32_e32 v1, v189
	v_mov_b32_e32 v145, v0
	v_and_b32_e32 v2, 15, v1
	v_ashrrev_i32_e32 v3, 2, v1
	v_and_b32_e32 v3, 0xffffffc0, v3
	v_lshrrev_b32_e32 v144, 1, v1
	v_or_b32_e32 v1, s13, v2
	v_add_u32_e32 v1, v1, v3
	v_and_b32_e32 v146, 0x78, v144
	v_and_b32_e32 v144, 24, v144
	v_ashrrev_i32_e32 v152, 4, v1
	v_lshlrev_b32_e32 v2, 5, v2
	v_mov_b32_e32 v3, v0
	v_lshl_add_u64 v[144:145], s[6:7], 0, v[144:145]
	s_add_i32 s2, s11, s59
	v_ashrrev_i32_e32 v153, 31, v152
	v_lshl_add_u64 v[148:149], v[144:145], 0, v[2:3]
	v_add_u32_e32 v146, s2, v146
	v_lshlrev_b64 v[2:3], 16, v[152:153]
	v_lshl_add_u64 v[154:155], v[148:149], 0, v[2:3]
	v_add_u32_e32 v2, 0x200, v146
	v_ashrrev_i32_e32 v2, 5, v2
	v_ashrrev_i32_e32 v3, 31, v2
	v_lshlrev_b64 v[2:3], 9, v[2:3]
	v_lshl_add_u64 v[144:145], v[154:155], 0, v[2:3]
	v_add_u32_e32 v147, 0xfffffe80, v146
	global_load_dwordx2 v[172:173], v[144:145], off
	v_add_u32_e32 v144, 0xfffffe00, v146
	v_add_u32_e32 v150, 0x280, v146
	v_ashrrev_i32_e32 v146, 5, v147
	v_ashrrev_i32_e32 v144, 5, v144
	v_ashrrev_i32_e32 v158, 5, v150
	v_ashrrev_i32_e32 v147, 31, v146
	v_ashrrev_i32_e32 v145, 31, v144
	v_ashrrev_i32_e32 v159, 31, v158
	v_lshlrev_b64 v[150:151], 9, v[146:147]
	v_lshlrev_b64 v[144:145], 9, v[144:145]
	v_lshlrev_b64 v[146:147], 9, v[158:159]
	v_lshl_add_u64 v[158:159], v[154:155], 0, v[150:151]
	v_lshl_add_u64 v[156:157], v[154:155], 0, v[144:145]
	v_lshl_add_u64 v[154:155], v[154:155], 0, v[146:147]
	global_load_dwordx2 v[174:175], v[158:159], off
	global_load_dwordx2 v[176:177], v[154:155], off
	global_load_dwordx2 v[180:181], v[156:157], off
	v_or_b32_e32 v154, 1, v152
	v_or_b32_e32 v156, 2, v152
	v_or_b32_e32 v152, 3, v152
	v_ashrrev_i32_e32 v155, 31, v154
	v_ashrrev_i32_e32 v157, 31, v156
	v_ashrrev_i32_e32 v153, 31, v152
	v_lshlrev_b64 v[154:155], 16, v[154:155]
	v_lshlrev_b64 v[156:157], 16, v[156:157]
	v_lshlrev_b64 v[152:153], 16, v[152:153]
	v_lshl_add_u64 v[154:155], v[148:149], 0, v[154:155]
	v_lshl_add_u64 v[156:157], v[148:149], 0, v[156:157]
	v_lshl_add_u64 v[152:153], v[148:149], 0, v[152:153]
	v_lshl_add_u64 v[158:159], v[154:155], 0, v[144:145]
	v_lshl_add_u64 v[160:161], v[154:155], 0, v[2:3]
	v_lshl_add_u64 v[162:163], v[154:155], 0, v[150:151]
	v_lshl_add_u64 v[154:155], v[154:155], 0, v[146:147]
	v_lshl_add_u64 v[164:165], v[156:157], 0, v[144:145]
	v_lshl_add_u64 v[166:167], v[156:157], 0, v[2:3]
	v_lshl_add_u64 v[182:183], v[156:157], 0, v[150:151]
	v_lshl_add_u64 v[156:157], v[156:157], 0, v[146:147]
	v_lshl_add_u64 v[184:185], v[152:153], 0, v[144:145]
	v_lshl_add_u64 v[186:187], v[152:153], 0, v[2:3]
	v_lshl_add_u64 v[190:191], v[152:153], 0, v[150:151]
	v_lshl_add_u64 v[192:193], v[152:153], 0, v[146:147]
	global_load_dwordx2 v[194:195], v[158:159], off
	global_load_dwordx2 v[196:197], v[160:161], off
	global_load_dwordx2 v[168:169], v[162:163], off
	global_load_dwordx2 v[170:171], v[154:155], off
	s_nop 0
	global_load_dwordx2 v[164:165], v[164:165], off
	s_nop 0
	global_load_dwordx2 v[166:167], v[166:167], off
	s_nop 0
	global_load_dwordx2 v[160:161], v[182:183], off
	global_load_dwordx2 v[162:163], v[156:157], off
	s_nop 0
	global_load_dwordx2 v[156:157], v[184:185], off
	global_load_dwordx2 v[158:159], v[186:187], off
	global_load_dwordx2 v[152:153], v[190:191], off
	global_load_dwordx2 v[154:155], v[192:193], off
	s_waitcnt vmcnt(0)
; __device__ __forceinline__ float fast_rcp(float x) { return __builtin_amdgcn_rcpf(x); }
;     __device__ __forceinline__ void hook(f32x4 (&acc)[2][2][4][2], const Unit& u, int nb, int wr, int wc, int fr, int fq) const {
;     ...
; #pragma unroll
;             for (int m = 0; m < 4; ++m)
; #pragma unroll
;                 for (int bj = 0; bj < 2; ++bj)
; #pragma unroll
;                     for (int e = 0; e < 8; ++e) { const unsigned qa = ((e < 4 ? ga[m][bj].x : ga[m][bj].y) >> (8 * (e & 3))) & 255u, qb = ((e < 4 ? gb[m][bj].x : gb[m][bj].y) >> (8 * (e & 3))) & 255u;
;                         acc[ai][bj][m][e >> 2][e & 3] *= ((float)qa + 0.5f) * fast_rcp((float)qb + 0.5f); }
	v_cvt_f32_ubyte0_e32 v182, v172
	v_cvt_f32_ubyte1_e32 v183, v172
	v_add_f32_e32 v182, 0.5, v182
	v_add_f32_e32 v183, 0.5, v183
	v_rcp_f32_e32 v182, v182
	v_rcp_f32_e32 v183, v183
	v_cvt_f32_ubyte2_e32 v184, v172
	v_cvt_f32_ubyte3_e32 v172, v172
	v_add_f32_e32 v172, 0.5, v172
	v_rcp_f32_e32 v185, v172
	v_cvt_f32_ubyte0_e32 v172, v173
	v_add_f32_e32 v172, 0.5, v172
	v_add_f32_e32 v184, 0.5, v184
	v_rcp_f32_e32 v184, v184
	v_cvt_f32_ubyte1_e32 v187, v180
	v_cvt_f32_ubyte0_e32 v186, v180
	v_pk_add_f32 v[186:187], v[186:187], 0.5 op_sel_hi:[1,0]
	v_cvt_f32_ubyte3_e32 v191, v180
	v_pk_mul_f32 v[182:183], v[186:187], v[182:183]
	v_cvt_f32_ubyte2_e32 v190, v180
	v_pk_mul_f32 v[128:129], v[128:129], v[182:183]
	v_rcp_f32_e32 v182, v172
	v_cvt_f32_ubyte1_e32 v172, v173
	v_add_f32_e32 v172, 0.5, v172
	v_rcp_f32_e32 v183, v172
	v_cvt_f32_ubyte2_e32 v172, v173
	v_cvt_f32_ubyte3_e32 v173, v173
	v_add_f32_e32 v172, 0.5, v172
	v_add_f32_e32 v173, 0.5, v173
	v_rcp_f32_e32 v172, v172
	v_rcp_f32_e32 v173, v173
	v_pk_add_f32 v[190:191], v[190:191], 0.5 op_sel_hi:[1,0]
	v_cvt_f32_ubyte3_e32 v187, v181
	v_pk_mul_f32 v[184:185], v[190:191], v[184:185]
	v_cvt_f32_ubyte2_e32 v186, v181
	v_pk_mul_f32 v[130:131], v[130:131], v[184:185]
	v_cvt_f32_ubyte1_e32 v185, v181
	v_cvt_f32_ubyte0_e32 v184, v181
	v_pk_add_f32 v[180:181], v[186:187], 0.5 op_sel_hi:[1,0]
	v_pk_add_f32 v[184:185], v[184:185], 0.5 op_sel_hi:[1,0]
	v_pk_mul_f32 v[172:173], v[180:181], v[172:173]
	v_pk_mul_f32 v[182:183], v[184:185], v[182:183]
	v_pk_mul_f32 v[126:127], v[126:127], v[172:173]
	v_cvt_f32_ubyte0_e32 v172, v176
	v_cvt_f32_ubyte1_e32 v173, v176
	v_add_f32_e32 v172, 0.5, v172
	v_add_f32_e32 v173, 0.5, v173
	v_rcp_f32_e32 v172, v172
	v_rcp_f32_e32 v173, v173
	v_pk_mul_f32 v[124:125], v[124:125], v[182:183]
	v_cvt_f32_ubyte2_e32 v180, v176
	v_cvt_f32_ubyte3_e32 v176, v176
	v_cvt_f32_ubyte1_e32 v183, v174
	v_cvt_f32_ubyte0_e32 v182, v174
	v_add_f32_e32 v180, 0.5, v180
	v_add_f32_e32 v176, 0.5, v176
	v_pk_add_f32 v[182:183], v[182:183], 0.5 op_sel_hi:[1,0]
	v_rcp_f32_e32 v180, v180
	v_rcp_f32_e32 v181, v176
	v_pk_mul_f32 v[172:173], v[182:183], v[172:173]
	v_cvt_f32_ubyte3_e32 v185, v174
	v_pk_mul_f32 v[120:121], v[120:121], v[172:173]
	v_cvt_f32_ubyte0_e32 v172, v177
	v_cvt_f32_ubyte1_e32 v173, v177
	v_cvt_f32_ubyte2_e32 v184, v174
	v_add_f32_e32 v172, 0.5, v172
	v_add_f32_e32 v173, 0.5, v173
	v_pk_add_f32 v[184:185], v[184:185], 0.5 op_sel_hi:[1,0]
	v_rcp_f32_e32 v172, v172
	v_rcp_f32_e32 v173, v173
	v_pk_mul_f32 v[180:181], v[184:185], v[180:181]
	v_cvt_f32_ubyte2_e32 v174, v177
	v_pk_mul_f32 v[122:123], v[122:123], v[180:181]
	v_add_f32_e32 v174, 0.5, v174
	v_cvt_f32_ubyte1_e32 v181, v175
	v_cvt_f32_ubyte0_e32 v180, v175
	v_rcp_f32_e32 v176, v174
	v_cvt_f32_ubyte3_e32 v174, v177
	v_pk_add_f32 v[180:181], v[180:181], 0.5 op_sel_hi:[1,0]
	v_add_f32_e32 v174, 0.5, v174
	v_pk_mul_f32 v[172:173], v[180:181], v[172:173]
	v_rcp_f32_e32 v177, v174
	v_pk_mul_f32 v[116:117], v[116:117], v[172:173]
	v_cvt_f32_ubyte0_e32 v172, v196
	v_cvt_f32_ubyte1_e32 v173, v196
	v_add_f32_e32 v172, 0.5, v172
	v_add_f32_e32 v173, 0.5, v173
	v_cvt_f32_ubyte3_e32 v183, v175
	v_cvt_f32_ubyte2_e32 v182, v175
	v_rcp_f32_e32 v172, v172
	v_rcp_f32_e32 v173, v173
	v_pk_add_f32 v[174:175], v[182:183], 0.5 op_sel_hi:[1,0]
	v_cvt_f32_ubyte3_e32 v181, v194
	v_pk_mul_f32 v[174:175], v[174:175], v[176:177]
	v_cvt_f32_ubyte1_e32 v177, v194
	v_cvt_f32_ubyte0_e32 v176, v194
	v_pk_add_f32 v[176:177], v[176:177], 0.5 op_sel_hi:[1,0]
	v_pk_mul_f32 v[118:119], v[118:119], v[174:175]
	v_cvt_f32_ubyte2_e32 v174, v196
	v_cvt_f32_ubyte3_e32 v175, v196
	v_pk_mul_f32 v[172:173], v[176:177], v[172:173]
	v_add_f32_e32 v174, 0.5, v174
	v_add_f32_e32 v175, 0.5, v175
	v_pk_mul_f32 v[112:113], v[112:113], v[172:173]
	v_cvt_f32_ubyte0_e32 v172, v197
	v_cvt_f32_ubyte1_e32 v173, v197
	v_rcp_f32_e32 v174, v174
	v_rcp_f32_e32 v175, v175
	v_add_f32_e32 v172, 0.5, v172
	v_add_f32_e32 v173, 0.5, v173
	v_rcp_f32_e32 v172, v172
	v_rcp_f32_e32 v173, v173
	v_cvt_f32_ubyte2_e32 v180, v194
	v_pk_add_f32 v[180:181], v[180:181], 0.5 op_sel_hi:[1,0]
	v_cvt_f32_ubyte1_e32 v177, v195
	v_cvt_f32_ubyte0_e32 v176, v195
	v_pk_mul_f32 v[174:175], v[180:181], v[174:175]
	v_pk_add_f32 v[176:177], v[176:177], 0.5 op_sel_hi:[1,0]
	v_pk_mul_f32 v[114:115], v[114:115], v[174:175]
	v_cvt_f32_ubyte2_e32 v174, v197
	v_cvt_f32_ubyte3_e32 v175, v197
	v_pk_mul_f32 v[172:173], v[176:177], v[172:173]
	v_add_f32_e32 v174, 0.5, v174
	v_add_f32_e32 v175, 0.5, v175
	v_pk_mul_f32 v[108:109], v[108:109], v[172:173]
	v_cvt_f32_ubyte0_e32 v172, v170
	v_cvt_f32_ubyte1_e32 v173, v170
	v_rcp_f32_e32 v174, v174
	v_rcp_f32_e32 v175, v175
	v_add_f32_e32 v172, 0.5, v172
	v_add_f32_e32 v173, 0.5, v173
	v_rcp_f32_e32 v172, v172
	v_rcp_f32_e32 v173, v173
	v_cvt_f32_ubyte3_e32 v181, v195
	v_cvt_f32_ubyte2_e32 v180, v195
	v_pk_add_f32 v[180:181], v[180:181], 0.5 op_sel_hi:[1,0]
	v_cvt_f32_ubyte1_e32 v177, v168
	v_cvt_f32_ubyte0_e32 v176, v168
	v_pk_mul_f32 v[174:175], v[180:181], v[174:175]
	v_cvt_f32_ubyte3_e32 v181, v168
	v_cvt_f32_ubyte2_e32 v180, v168
	v_pk_add_f32 v[176:177], v[176:177], 0.5 op_sel_hi:[1,0]
	v_cvt_f32_ubyte0_e32 v168, v171
	v_pk_mul_f32 v[172:173], v[176:177], v[172:173]
	v_add_f32_e32 v168, 0.5, v168
	v_pk_mul_f32 v[104:105], v[104:105], v[172:173]
	v_rcp_f32_e32 v172, v168
	v_cvt_f32_ubyte1_e32 v168, v171
	v_add_f32_e32 v168, 0.5, v168
	v_pk_mul_f32 v[110:111], v[110:111], v[174:175]
	v_cvt_f32_ubyte2_e32 v174, v170
	v_cvt_f32_ubyte3_e32 v170, v170
	v_rcp_f32_e32 v173, v168
	v_cvt_f32_ubyte2_e32 v168, v171
	v_add_f32_e32 v174, 0.5, v174
	v_add_f32_e32 v170, 0.5, v170
; __device__ __forceinline__ float fast_rcp(float x) { return __builtin_amdgcn_rcpf(x); }
;     __device__ __forceinline__ void hook(f32x4 (&acc)[2][2][4][2], const Unit& u, int nb, int wr, int wc, int fr, int fq) const {
;     ...
; #pragma unroll
;             for (int m = 0; m < 4; ++m)
; #pragma unroll
;                 for (int bj = 0; bj < 2; ++bj)
; #pragma unroll
;                     for (int e = 0; e < 8; ++e) { const unsigned qa = ((e < 4 ? ga[m][bj].x : ga[m][bj].y) >> (8 * (e & 3))) & 255u, qb = ((e < 4 ? gb[m][bj].x : gb[m][bj].y) >> (8 * (e & 3))) & 255u;
;                         acc[ai][bj][m][e >> 2][e & 3] *= ((float)qa + 0.5f) * fast_rcp((float)qb + 0.5f); }
	v_add_f32_e32 v168, 0.5, v168
	v_rcp_f32_e32 v174, v174
	v_rcp_f32_e32 v175, v170
	v_rcp_f32_e32 v170, v168
	v_cvt_f32_ubyte3_e32 v168, v171
	v_add_f32_e32 v168, 0.5, v168
	v_rcp_f32_e32 v171, v168
	v_pk_add_f32 v[180:181], v[180:181], 0.5 op_sel_hi:[1,0]
	v_cvt_f32_ubyte3_e32 v177, v169
	v_pk_mul_f32 v[174:175], v[180:181], v[174:175]
	v_cvt_f32_ubyte2_e32 v176, v169
	v_pk_mul_f32 v[106:107], v[106:107], v[174:175]
	v_cvt_f32_ubyte1_e32 v175, v169
	v_cvt_f32_ubyte0_e32 v174, v169
	v_pk_add_f32 v[168:169], v[176:177], 0.5 op_sel_hi:[1,0]
	v_pk_add_f32 v[174:175], v[174:175], 0.5 op_sel_hi:[1,0]
	v_pk_mul_f32 v[168:169], v[168:169], v[170:171]
	v_pk_mul_f32 v[172:173], v[174:175], v[172:173]
	v_pk_mul_f32 v[102:103], v[102:103], v[168:169]
	v_cvt_f32_ubyte0_e32 v168, v166
	v_cvt_f32_ubyte1_e32 v169, v166
	v_add_f32_e32 v168, 0.5, v168
	v_add_f32_e32 v169, 0.5, v169
	v_rcp_f32_e32 v168, v168
	v_rcp_f32_e32 v169, v169
	v_pk_mul_f32 v[100:101], v[100:101], v[172:173]
	v_cvt_f32_ubyte1_e32 v173, v164
	v_cvt_f32_ubyte0_e32 v172, v164
	v_cvt_f32_ubyte3_e32 v175, v164
	v_cvt_f32_ubyte2_e32 v174, v164
	v_pk_add_f32 v[172:173], v[172:173], 0.5 op_sel_hi:[1,0]
	v_cvt_f32_ubyte0_e32 v164, v167
	v_pk_mul_f32 v[168:169], v[172:173], v[168:169]
	v_add_f32_e32 v164, 0.5, v164
	v_pk_mul_f32 v[96:97], v[96:97], v[168:169]
	v_rcp_f32_e32 v168, v164
	v_cvt_f32_ubyte1_e32 v164, v167
	v_add_f32_e32 v164, 0.5, v164
	v_cvt_f32_ubyte2_e32 v170, v166
	v_cvt_f32_ubyte3_e32 v166, v166
	v_rcp_f32_e32 v169, v164
	v_cvt_f32_ubyte2_e32 v164, v167
	v_add_f32_e32 v170, 0.5, v170
	v_add_f32_e32 v166, 0.5, v166
	v_add_f32_e32 v164, 0.5, v164
	v_rcp_f32_e32 v170, v170
	v_rcp_f32_e32 v171, v166
	v_rcp_f32_e32 v166, v164
	v_cvt_f32_ubyte3_e32 v164, v167
	v_add_f32_e32 v164, 0.5, v164
	v_rcp_f32_e32 v167, v164
	v_pk_add_f32 v[174:175], v[174:175], 0.5 op_sel_hi:[1,0]
	v_cvt_f32_ubyte3_e32 v173, v165
	v_pk_mul_f32 v[170:171], v[174:175], v[170:171]
	v_cvt_f32_ubyte2_e32 v172, v165
	v_pk_mul_f32 v[98:99], v[98:99], v[170:171]
	v_cvt_f32_ubyte1_e32 v171, v165
	v_cvt_f32_ubyte0_e32 v170, v165
	v_pk_add_f32 v[164:165], v[172:173], 0.5 op_sel_hi:[1,0]
	v_pk_add_f32 v[170:171], v[170:171], 0.5 op_sel_hi:[1,0]
	v_pk_mul_f32 v[164:165], v[164:165], v[166:167]
	v_pk_mul_f32 v[168:169], v[170:171], v[168:169]
	v_pk_mul_f32 v[94:95], v[94:95], v[164:165]
	v_cvt_f32_ubyte0_e32 v164, v162
	v_cvt_f32_ubyte1_e32 v165, v162
	v_add_f32_e32 v164, 0.5, v164
	v_add_f32_e32 v165, 0.5, v165
	v_rcp_f32_e32 v164, v164
	v_rcp_f32_e32 v165, v165
	v_pk_mul_f32 v[92:93], v[92:93], v[168:169]
	v_cvt_f32_ubyte1_e32 v169, v160
	v_cvt_f32_ubyte0_e32 v168, v160
	v_cvt_f32_ubyte3_e32 v171, v160
	v_cvt_f32_ubyte2_e32 v170, v160
	v_pk_add_f32 v[168:169], v[168:169], 0.5 op_sel_hi:[1,0]
	v_cvt_f32_ubyte0_e32 v160, v163
	v_pk_mul_f32 v[164:165], v[168:169], v[164:165]
	v_add_f32_e32 v160, 0.5, v160
	v_pk_mul_f32 v[88:89], v[88:89], v[164:165]
	v_rcp_f32_e32 v164, v160
	v_cvt_f32_ubyte1_e32 v160, v163
	v_add_f32_e32 v160, 0.5, v160
	v_cvt_f32_ubyte2_e32 v166, v162
	v_cvt_f32_ubyte3_e32 v162, v162
	v_rcp_f32_e32 v165, v160
	v_cvt_f32_ubyte2_e32 v160, v163
	v_add_f32_e32 v166, 0.5, v166
	v_add_f32_e32 v162, 0.5, v162
	v_add_f32_e32 v160, 0.5, v160
	v_rcp_f32_e32 v166, v166
	v_rcp_f32_e32 v167, v162
	v_rcp_f32_e32 v162, v160
	v_cvt_f32_ubyte3_e32 v160, v163
	v_add_f32_e32 v160, 0.5, v160
	v_rcp_f32_e32 v163, v160
	v_pk_add_f32 v[170:171], v[170:171], 0.5 op_sel_hi:[1,0]
	v_cvt_f32_ubyte3_e32 v169, v161
	v_pk_mul_f32 v[166:167], v[170:171], v[166:167]
	v_cvt_f32_ubyte2_e32 v168, v161
	v_pk_mul_f32 v[90:91], v[90:91], v[166:167]
	v_cvt_f32_ubyte1_e32 v167, v161
	v_cvt_f32_ubyte0_e32 v166, v161
	v_pk_add_f32 v[160:161], v[168:169], 0.5 op_sel_hi:[1,0]
	v_pk_add_f32 v[166:167], v[166:167], 0.5 op_sel_hi:[1,0]
	v_pk_mul_f32 v[160:161], v[160:161], v[162:163]
	v_pk_mul_f32 v[164:165], v[166:167], v[164:165]
	v_pk_mul_f32 v[86:87], v[86:87], v[160:161]
	v_cvt_f32_ubyte0_e32 v160, v158
	v_cvt_f32_ubyte1_e32 v161, v158
	v_add_f32_e32 v160, 0.5, v160
	v_add_f32_e32 v161, 0.5, v161
	v_rcp_f32_e32 v160, v160
	v_rcp_f32_e32 v161, v161
	v_pk_mul_f32 v[84:85], v[84:85], v[164:165]
	v_cvt_f32_ubyte1_e32 v165, v156
	v_cvt_f32_ubyte0_e32 v164, v156
	v_cvt_f32_ubyte3_e32 v167, v156
	v_cvt_f32_ubyte2_e32 v166, v156
	v_pk_add_f32 v[164:165], v[164:165], 0.5 op_sel_hi:[1,0]
	v_cvt_f32_ubyte0_e32 v156, v159
	v_pk_mul_f32 v[160:161], v[164:165], v[160:161]
	v_add_f32_e32 v156, 0.5, v156
	v_pk_mul_f32 v[80:81], v[80:81], v[160:161]
	v_rcp_f32_e32 v160, v156
	v_cvt_f32_ubyte1_e32 v156, v159
	v_add_f32_e32 v156, 0.5, v156
	v_cvt_f32_ubyte2_e32 v162, v158
	v_cvt_f32_ubyte3_e32 v158, v158
	v_rcp_f32_e32 v161, v156
	v_cvt_f32_ubyte2_e32 v156, v159
	v_add_f32_e32 v162, 0.5, v162
	v_add_f32_e32 v158, 0.5, v158
	v_add_f32_e32 v156, 0.5, v156
	v_rcp_f32_e32 v162, v162
	v_rcp_f32_e32 v163, v158
	v_rcp_f32_e32 v158, v156
	v_cvt_f32_ubyte3_e32 v156, v159
	v_add_f32_e32 v156, 0.5, v156
	v_rcp_f32_e32 v159, v156
	v_pk_add_f32 v[166:167], v[166:167], 0.5 op_sel_hi:[1,0]
	v_cvt_f32_ubyte3_e32 v165, v157
	v_pk_mul_f32 v[162:163], v[166:167], v[162:163]
	v_cvt_f32_ubyte2_e32 v164, v157
	v_pk_mul_f32 v[82:83], v[82:83], v[162:163]
	v_cvt_f32_ubyte1_e32 v163, v157
	v_cvt_f32_ubyte0_e32 v162, v157
	v_pk_add_f32 v[156:157], v[164:165], 0.5 op_sel_hi:[1,0]
	v_pk_add_f32 v[162:163], v[162:163], 0.5 op_sel_hi:[1,0]
	v_pk_mul_f32 v[156:157], v[156:157], v[158:159]
	v_pk_mul_f32 v[160:161], v[162:163], v[160:161]
	v_pk_mul_f32 v[78:79], v[78:79], v[156:157]
	v_cvt_f32_ubyte0_e32 v156, v154
	v_cvt_f32_ubyte1_e32 v157, v154
	v_add_f32_e32 v156, 0.5, v156
; __device__ __forceinline__ float fast_rcp(float x) { return __builtin_amdgcn_rcpf(x); }
; __device__ __forceinline__ size_t g8_off(int row, int colg) { return ((size_t)(row >> 4) * 128 + (colg >> 5)) * 512 + (row & 15) * 32 + (colg & 31); }
;     __device__ __forceinline__ void hook(f32x4 (&acc)[2][2][4][2], const Unit& u, int nb, int wr, int wc, int fr, int fq) const {
;     ...
;         for (int ai = 0; ai < 2; ++ai) {
;             u32x2 ga[4][2], gb[4][2];
; #pragma unroll
;             for (int m = 0; m < 4; ++m)
; #pragma unroll
;                 for (int bj = 0; bj < 2; ++bj) { const int row = row0 + ai * 128 + m * 16, c = c0 + bj * 128;
;                     ga[m][bj] = *(const u32x2*)(G8 + g8_off(row, (nb - 1) * 1024 + c)); gb[m][bj] = *(const u32x2*)(G8 + g8_off(row, nb * 1024 + c)); }
; #pragma unroll
;             for (int m = 0; m < 4; ++m)
; #pragma unroll
;                 for (int bj = 0; bj < 2; ++bj)
; #pragma unroll
;                     for (int e = 0; e < 8; ++e) { const unsigned qa = ((e < 4 ? ga[m][bj].x : ga[m][bj].y) >> (8 * (e & 3))) & 255u, qb = ((e < 4 ? gb[m][bj].x : gb[m][bj].y) >> (8 * (e & 3))) & 255u;
;                         acc[ai][bj][m][e >> 2][e & 3] *= ((float)qa + 0.5f) * fast_rcp((float)qb + 0.5f); }
	v_add_f32_e32 v157, 0.5, v157
	v_rcp_f32_e32 v156, v156
	v_rcp_f32_e32 v157, v157
	v_pk_mul_f32 v[76:77], v[76:77], v[160:161]
	v_cvt_f32_ubyte1_e32 v161, v152
	v_cvt_f32_ubyte0_e32 v160, v152
	v_cvt_f32_ubyte3_e32 v163, v152
	v_cvt_f32_ubyte2_e32 v162, v152
	v_pk_add_f32 v[160:161], v[160:161], 0.5 op_sel_hi:[1,0]
	v_cvt_f32_ubyte0_e32 v152, v155
	v_pk_mul_f32 v[156:157], v[160:161], v[156:157]
	v_add_f32_e32 v152, 0.5, v152
	v_pk_mul_f32 v[72:73], v[72:73], v[156:157]
	v_rcp_f32_e32 v156, v152
	v_cvt_f32_ubyte1_e32 v152, v155
	v_cvt_f32_ubyte2_e32 v158, v154
	v_cvt_f32_ubyte3_e32 v154, v154
	v_add_f32_e32 v152, 0.5, v152
	v_add_f32_e32 v158, 0.5, v158
	v_add_f32_e32 v154, 0.5, v154
	v_rcp_f32_e32 v157, v152
	v_cvt_f32_ubyte2_e32 v152, v155
	v_rcp_f32_e32 v158, v158
	v_rcp_f32_e32 v159, v154
	v_add_f32_e32 v152, 0.5, v152
	v_rcp_f32_e32 v154, v152
	v_cvt_f32_ubyte3_e32 v152, v155
	v_add_f32_e32 v152, 0.5, v152
	v_pk_add_f32 v[162:163], v[162:163], 0.5 op_sel_hi:[1,0]
	v_rcp_f32_e32 v155, v152
	v_pk_mul_f32 v[158:159], v[162:163], v[158:159]
	v_cvt_f32_ubyte3_e32 v161, v153
	v_pk_mul_f32 v[74:75], v[74:75], v[158:159]
	v_cvt_f32_ubyte1_e32 v159, v153
	v_cvt_f32_ubyte0_e32 v158, v153
	v_cvt_f32_ubyte2_e32 v160, v153
	v_pk_add_f32 v[152:153], v[160:161], 0.5 op_sel_hi:[1,0]
	v_pk_add_f32 v[158:159], v[158:159], 0.5 op_sel_hi:[1,0]
	v_pk_mul_f32 v[152:153], v[152:153], v[154:155]
	v_pk_mul_f32 v[156:157], v[158:159], v[156:157]
	v_pk_mul_f32 v[70:71], v[70:71], v[152:153]
	v_pk_mul_f32 v[68:69], v[68:69], v[156:157]
	v_add_u32_e32 v152, 0x80, v1
	v_ashrrev_i32_e32 v152, 4, v152
	v_ashrrev_i32_e32 v153, 31, v152
	v_lshlrev_b64 v[152:153], 16, v[152:153]
	v_lshl_add_u64 v[152:153], v[148:149], 0, v[152:153]
	v_lshl_add_u64 v[154:155], v[152:153], 0, v[144:145]
	global_load_dwordx2 v[174:175], v[154:155], off
	v_lshl_add_u64 v[154:155], v[152:153], 0, v[2:3]
	global_load_dwordx2 v[176:177], v[154:155], off
	v_lshl_add_u64 v[154:155], v[152:153], 0, v[150:151]
	v_lshl_add_u64 v[152:153], v[152:153], 0, v[146:147]
	global_load_dwordx2 v[170:171], v[154:155], off
	global_load_dwordx2 v[172:173], v[152:153], off
	v_add_u32_e32 v152, 0x90, v1
	v_ashrrev_i32_e32 v152, 4, v152
	v_ashrrev_i32_e32 v153, 31, v152
	v_lshlrev_b64 v[152:153], 16, v[152:153]
	v_lshl_add_u64 v[152:153], v[148:149], 0, v[152:153]
	v_lshl_add_u64 v[154:155], v[152:153], 0, v[144:145]
	global_load_dwordx2 v[166:167], v[154:155], off
	v_lshl_add_u64 v[154:155], v[152:153], 0, v[2:3]
	global_load_dwordx2 v[168:169], v[154:155], off
	v_lshl_add_u64 v[154:155], v[152:153], 0, v[150:151]
	v_lshl_add_u64 v[152:153], v[152:153], 0, v[146:147]
	global_load_dwordx2 v[162:163], v[154:155], off
	global_load_dwordx2 v[164:165], v[152:153], off
	v_add_u32_e32 v152, 0xa0, v1
	v_add_u32_e32 v1, 0xb0, v1
	v_ashrrev_i32_e32 v152, 4, v152
	v_ashrrev_i32_e32 v160, 4, v1
	v_ashrrev_i32_e32 v153, 31, v152
	v_ashrrev_i32_e32 v161, 31, v160
	v_lshlrev_b64 v[152:153], 16, v[152:153]
	v_lshlrev_b64 v[160:161], 16, v[160:161]
	v_lshl_add_u64 v[154:155], v[148:149], 0, v[152:153]
	v_lshl_add_u64 v[180:181], v[148:149], 0, v[160:161]
	v_lshl_add_u64 v[152:153], v[154:155], 0, v[144:145]
	v_lshl_add_u64 v[144:145], v[180:181], 0, v[144:145]
	global_load_dwordx2 v[156:157], v[152:153], off
	global_load_dwordx2 v[148:149], v[144:145], off
	v_lshl_add_u64 v[152:153], v[154:155], 0, v[2:3]
	global_load_dwordx2 v[158:159], v[152:153], off
	v_lshl_add_u64 v[2:3], v[180:181], 0, v[2:3]
	global_load_dwordx2 v[160:161], v[2:3], off
	v_lshl_add_u64 v[2:3], v[180:181], 0, v[150:151]
	v_lshl_add_u64 v[144:145], v[180:181], 0, v[146:147]
	global_load_dwordx2 v[2:3], v[2:3], off
	global_load_dwordx2 v[144:145], v[144:145], off
	v_lshl_add_u64 v[152:153], v[154:155], 0, v[150:151]
	v_lshl_add_u64 v[154:155], v[154:155], 0, v[146:147]
	global_load_dwordx2 v[152:153], v[152:153], off
	s_nop 0
	global_load_dwordx2 v[154:155], v[154:155], off
	s_waitcnt vmcnt(0)
	v_cvt_f32_ubyte1_e32 v181, v174
	v_cvt_f32_ubyte0_e32 v1, v176
	v_add_f32_e32 v1, 0.5, v1
	v_rcp_f32_e32 v146, v1
	v_cvt_f32_ubyte1_e32 v1, v176
	v_add_f32_e32 v1, 0.5, v1
	v_rcp_f32_e32 v147, v1
	v_cvt_f32_ubyte2_e32 v1, v176
	v_add_f32_e32 v1, 0.5, v1
	v_rcp_f32_e32 v150, v1
	v_cvt_f32_ubyte3_e32 v1, v176
	v_add_f32_e32 v1, 0.5, v1
	v_cvt_f32_ubyte0_e32 v180, v174
	v_rcp_f32_e32 v151, v1
	v_pk_add_f32 v[180:181], v[180:181], 0.5 op_sel_hi:[1,0]
	v_cvt_f32_ubyte0_e32 v1, v177
	v_pk_mul_f32 v[146:147], v[180:181], v[146:147]
	v_add_f32_e32 v1, 0.5, v1
	v_pk_mul_f32 v[64:65], v[64:65], v[146:147]
	v_rcp_f32_e32 v146, v1
	v_cvt_f32_ubyte1_e32 v1, v177
	v_cvt_f32_ubyte3_e32 v183, v174
	v_cvt_f32_ubyte2_e32 v182, v174
	v_add_f32_e32 v1, 0.5, v1
	v_pk_add_f32 v[182:183], v[182:183], 0.5 op_sel_hi:[1,0]
	v_rcp_f32_e32 v147, v1
	v_cvt_f32_ubyte2_e32 v1, v177
	v_pk_mul_f32 v[150:151], v[182:183], v[150:151]
	v_add_f32_e32 v1, 0.5, v1
	v_pk_mul_f32 v[66:67], v[66:67], v[150:151]
	v_rcp_f32_e32 v150, v1
	v_cvt_f32_ubyte3_e32 v1, v177
	v_add_f32_e32 v1, 0.5, v1
	v_cvt_f32_ubyte1_e32 v177, v175
	v_cvt_f32_ubyte0_e32 v176, v175
	v_rcp_f32_e32 v151, v1
	v_pk_add_f32 v[176:177], v[176:177], 0.5 op_sel_hi:[1,0]
	v_cvt_f32_ubyte0_e32 v1, v172
	v_pk_mul_f32 v[146:147], v[176:177], v[146:147]
	v_add_f32_e32 v1, 0.5, v1
	v_pk_mul_f32 v[60:61], v[60:61], v[146:147]
	v_rcp_f32_e32 v146, v1
	v_cvt_f32_ubyte1_e32 v1, v172
	v_cvt_f32_ubyte3_e32 v181, v175
	v_cvt_f32_ubyte2_e32 v180, v175
	v_add_f32_e32 v1, 0.5, v1
	v_pk_add_f32 v[174:175], v[180:181], 0.5 op_sel_hi:[1,0]
	v_rcp_f32_e32 v147, v1
	v_cvt_f32_ubyte2_e32 v1, v172
	v_pk_mul_f32 v[150:151], v[174:175], v[150:151]
; __device__ __forceinline__ float fast_rcp(float x) { return __builtin_amdgcn_rcpf(x); }
;     __device__ __forceinline__ void hook(f32x4 (&acc)[2][2][4][2], const Unit& u, int nb, int wr, int wc, int fr, int fq) const {
;     ...
; #pragma unroll
;             for (int m = 0; m < 4; ++m)
; #pragma unroll
;                 for (int bj = 0; bj < 2; ++bj)
; #pragma unroll
;                     for (int e = 0; e < 8; ++e) { const unsigned qa = ((e < 4 ? ga[m][bj].x : ga[m][bj].y) >> (8 * (e & 3))) & 255u, qb = ((e < 4 ? gb[m][bj].x : gb[m][bj].y) >> (8 * (e & 3))) & 255u;
;                         acc[ai][bj][m][e >> 2][e & 3] *= ((float)qa + 0.5f) * fast_rcp((float)qb + 0.5f); }
	v_add_f32_e32 v1, 0.5, v1
	v_pk_mul_f32 v[62:63], v[62:63], v[150:151]
	v_rcp_f32_e32 v150, v1
	v_cvt_f32_ubyte3_e32 v1, v172
	v_add_f32_e32 v1, 0.5, v1
	v_cvt_f32_ubyte1_e32 v175, v170
	v_cvt_f32_ubyte0_e32 v174, v170
	v_rcp_f32_e32 v151, v1
	v_pk_add_f32 v[174:175], v[174:175], 0.5 op_sel_hi:[1,0]
	v_cvt_f32_ubyte0_e32 v1, v173
	v_pk_mul_f32 v[146:147], v[174:175], v[146:147]
	v_add_f32_e32 v1, 0.5, v1
	v_pk_mul_f32 v[56:57], v[56:57], v[146:147]
	v_rcp_f32_e32 v146, v1
	v_cvt_f32_ubyte1_e32 v1, v173
	v_cvt_f32_ubyte3_e32 v177, v170
	v_cvt_f32_ubyte2_e32 v176, v170
	v_add_f32_e32 v1, 0.5, v1
	v_pk_add_f32 v[176:177], v[176:177], 0.5 op_sel_hi:[1,0]
	v_rcp_f32_e32 v147, v1
	v_cvt_f32_ubyte2_e32 v1, v173
	v_pk_mul_f32 v[150:151], v[176:177], v[150:151]
	v_add_f32_e32 v1, 0.5, v1
	v_pk_mul_f32 v[58:59], v[58:59], v[150:151]
	v_rcp_f32_e32 v150, v1
	v_cvt_f32_ubyte3_e32 v1, v173
	v_add_f32_e32 v1, 0.5, v1
	v_cvt_f32_ubyte1_e32 v173, v171
	v_cvt_f32_ubyte0_e32 v172, v171
	v_rcp_f32_e32 v151, v1
	v_pk_add_f32 v[172:173], v[172:173], 0.5 op_sel_hi:[1,0]
	v_cvt_f32_ubyte0_e32 v1, v168
	v_pk_mul_f32 v[146:147], v[172:173], v[146:147]
	v_add_f32_e32 v1, 0.5, v1
	v_pk_mul_f32 v[52:53], v[52:53], v[146:147]
	v_rcp_f32_e32 v146, v1
	v_cvt_f32_ubyte1_e32 v1, v168
	v_cvt_f32_ubyte3_e32 v175, v171
	v_cvt_f32_ubyte2_e32 v174, v171
	v_add_f32_e32 v1, 0.5, v1
	v_pk_add_f32 v[170:171], v[174:175], 0.5 op_sel_hi:[1,0]
	v_rcp_f32_e32 v147, v1
	v_cvt_f32_ubyte2_e32 v1, v168
	v_pk_mul_f32 v[150:151], v[170:171], v[150:151]
	v_add_f32_e32 v1, 0.5, v1
	v_pk_mul_f32 v[54:55], v[54:55], v[150:151]
	v_rcp_f32_e32 v150, v1
	v_cvt_f32_ubyte3_e32 v1, v168
	v_add_f32_e32 v1, 0.5, v1
	v_cvt_f32_ubyte1_e32 v171, v166
	v_cvt_f32_ubyte0_e32 v170, v166
	v_rcp_f32_e32 v151, v1
	v_pk_add_f32 v[170:171], v[170:171], 0.5 op_sel_hi:[1,0]
	v_cvt_f32_ubyte0_e32 v1, v169
	v_pk_mul_f32 v[146:147], v[170:171], v[146:147]
	v_add_f32_e32 v1, 0.5, v1
	v_pk_mul_f32 v[48:49], v[48:49], v[146:147]
	v_rcp_f32_e32 v146, v1
	v_cvt_f32_ubyte1_e32 v1, v169
	v_cvt_f32_ubyte3_e32 v173, v166
	v_cvt_f32_ubyte2_e32 v172, v166
	v_add_f32_e32 v1, 0.5, v1
	v_pk_add_f32 v[172:173], v[172:173], 0.5 op_sel_hi:[1,0]
	v_rcp_f32_e32 v147, v1
	v_cvt_f32_ubyte2_e32 v1, v169
	v_pk_mul_f32 v[150:151], v[172:173], v[150:151]
	v_add_f32_e32 v1, 0.5, v1
	v_pk_mul_f32 v[50:51], v[50:51], v[150:151]
	v_rcp_f32_e32 v150, v1
	v_cvt_f32_ubyte3_e32 v1, v169
	v_add_f32_e32 v1, 0.5, v1
	v_cvt_f32_ubyte1_e32 v169, v167
	v_cvt_f32_ubyte0_e32 v168, v167
	v_rcp_f32_e32 v151, v1
	v_pk_add_f32 v[168:169], v[168:169], 0.5 op_sel_hi:[1,0]
	v_cvt_f32_ubyte0_e32 v1, v164
	v_pk_mul_f32 v[146:147], v[168:169], v[146:147]
	v_add_f32_e32 v1, 0.5, v1
	v_pk_mul_f32 v[44:45], v[44:45], v[146:147]
	v_rcp_f32_e32 v146, v1
	v_cvt_f32_ubyte1_e32 v1, v164
	v_cvt_f32_ubyte3_e32 v171, v167
	v_cvt_f32_ubyte2_e32 v170, v167
	v_add_f32_e32 v1, 0.5, v1
	v_pk_add_f32 v[166:167], v[170:171], 0.5 op_sel_hi:[1,0]
	v_rcp_f32_e32 v147, v1
	v_cvt_f32_ubyte2_e32 v1, v164
	v_pk_mul_f32 v[150:151], v[166:167], v[150:151]
	v_add_f32_e32 v1, 0.5, v1
	v_pk_mul_f32 v[46:47], v[46:47], v[150:151]
	v_rcp_f32_e32 v150, v1
	v_cvt_f32_ubyte3_e32 v1, v164
	v_add_f32_e32 v1, 0.5, v1
	v_cvt_f32_ubyte1_e32 v167, v162
	v_cvt_f32_ubyte0_e32 v166, v162
	v_rcp_f32_e32 v151, v1
	v_pk_add_f32 v[166:167], v[166:167], 0.5 op_sel_hi:[1,0]
	v_cvt_f32_ubyte0_e32 v1, v165
	v_pk_mul_f32 v[146:147], v[166:167], v[146:147]
	v_add_f32_e32 v1, 0.5, v1
	v_pk_mul_f32 v[40:41], v[40:41], v[146:147]
	v_rcp_f32_e32 v146, v1
	v_cvt_f32_ubyte1_e32 v1, v165
	v_cvt_f32_ubyte3_e32 v169, v162
	v_cvt_f32_ubyte2_e32 v168, v162
	v_add_f32_e32 v1, 0.5, v1
	v_pk_add_f32 v[168:169], v[168:169], 0.5 op_sel_hi:[1,0]
	v_rcp_f32_e32 v147, v1
	v_cvt_f32_ubyte2_e32 v1, v165
	v_pk_mul_f32 v[150:151], v[168:169], v[150:151]
	v_add_f32_e32 v1, 0.5, v1
	v_pk_mul_f32 v[42:43], v[42:43], v[150:151]
	v_rcp_f32_e32 v150, v1
	v_cvt_f32_ubyte3_e32 v1, v165
	v_add_f32_e32 v1, 0.5, v1
	v_cvt_f32_ubyte1_e32 v165, v163
	v_cvt_f32_ubyte0_e32 v164, v163
	v_rcp_f32_e32 v151, v1
	v_pk_add_f32 v[164:165], v[164:165], 0.5 op_sel_hi:[1,0]
	v_cvt_f32_ubyte0_e32 v1, v158
	v_pk_mul_f32 v[146:147], v[164:165], v[146:147]
	v_add_f32_e32 v1, 0.5, v1
	v_pk_mul_f32 v[36:37], v[36:37], v[146:147]
	v_rcp_f32_e32 v146, v1
	v_cvt_f32_ubyte1_e32 v1, v158
	v_cvt_f32_ubyte3_e32 v167, v163
	v_cvt_f32_ubyte2_e32 v166, v163
	v_add_f32_e32 v1, 0.5, v1
	v_pk_add_f32 v[162:163], v[166:167], 0.5 op_sel_hi:[1,0]
	v_rcp_f32_e32 v147, v1
	v_cvt_f32_ubyte2_e32 v1, v158
	v_pk_mul_f32 v[150:151], v[162:163], v[150:151]
	v_add_f32_e32 v1, 0.5, v1
	v_pk_mul_f32 v[38:39], v[38:39], v[150:151]
	v_rcp_f32_e32 v150, v1
	v_cvt_f32_ubyte3_e32 v1, v158
	v_add_f32_e32 v1, 0.5, v1
	v_cvt_f32_ubyte1_e32 v163, v156
	v_cvt_f32_ubyte0_e32 v162, v156
	v_rcp_f32_e32 v151, v1
	v_pk_add_f32 v[162:163], v[162:163], 0.5 op_sel_hi:[1,0]
	v_cvt_f32_ubyte0_e32 v1, v159
	v_pk_mul_f32 v[146:147], v[162:163], v[146:147]
	v_add_f32_e32 v1, 0.5, v1
	v_pk_mul_f32 v[32:33], v[32:33], v[146:147]
	v_rcp_f32_e32 v146, v1
	v_cvt_f32_ubyte1_e32 v1, v159
	v_cvt_f32_ubyte3_e32 v165, v156
	v_cvt_f32_ubyte2_e32 v164, v156
	v_add_f32_e32 v1, 0.5, v1
	v_pk_add_f32 v[164:165], v[164:165], 0.5 op_sel_hi:[1,0]
	v_rcp_f32_e32 v147, v1
	v_cvt_f32_ubyte2_e32 v1, v159
	v_pk_mul_f32 v[150:151], v[164:165], v[150:151]
	v_add_f32_e32 v1, 0.5, v1
	v_pk_mul_f32 v[34:35], v[34:35], v[150:151]
	v_rcp_f32_e32 v150, v1
	v_cvt_f32_ubyte3_e32 v1, v159
	v_add_f32_e32 v1, 0.5, v1
	v_cvt_f32_ubyte1_e32 v159, v157
	v_cvt_f32_ubyte0_e32 v158, v157
	v_rcp_f32_e32 v151, v1
	v_pk_add_f32 v[158:159], v[158:159], 0.5 op_sel_hi:[1,0]
	s_waitcnt vmcnt(0)
; __device__ __forceinline__ float fast_rcp(float x) { return __builtin_amdgcn_rcpf(x); }
;     __device__ __forceinline__ void hook(f32x4 (&acc)[2][2][4][2], const Unit& u, int nb, int wr, int wc, int fr, int fq) const {
;     ...
; #pragma unroll
;             for (int m = 0; m < 4; ++m)
; #pragma unroll
;                 for (int bj = 0; bj < 2; ++bj)
; #pragma unroll
;                     for (int e = 0; e < 8; ++e) { const unsigned qa = ((e < 4 ? ga[m][bj].x : ga[m][bj].y) >> (8 * (e & 3))) & 255u, qb = ((e < 4 ? gb[m][bj].x : gb[m][bj].y) >> (8 * (e & 3))) & 255u;
;                         acc[ai][bj][m][e >> 2][e & 3] *= ((float)qa + 0.5f) * fast_rcp((float)qb + 0.5f); }
	v_cvt_f32_ubyte0_e32 v1, v154
	v_pk_mul_f32 v[146:147], v[158:159], v[146:147]
	v_add_f32_e32 v1, 0.5, v1
	v_pk_mul_f32 v[28:29], v[28:29], v[146:147]
	v_rcp_f32_e32 v146, v1
	v_cvt_f32_ubyte1_e32 v1, v154
	v_cvt_f32_ubyte3_e32 v163, v157
	v_cvt_f32_ubyte2_e32 v162, v157
	v_add_f32_e32 v1, 0.5, v1
	v_pk_add_f32 v[156:157], v[162:163], 0.5 op_sel_hi:[1,0]
	v_rcp_f32_e32 v147, v1
	v_cvt_f32_ubyte2_e32 v1, v154
	v_pk_mul_f32 v[150:151], v[156:157], v[150:151]
	v_add_f32_e32 v1, 0.5, v1
	v_pk_mul_f32 v[30:31], v[30:31], v[150:151]
	v_rcp_f32_e32 v150, v1
	v_cvt_f32_ubyte3_e32 v1, v154
	v_add_f32_e32 v1, 0.5, v1
	v_cvt_f32_ubyte1_e32 v157, v152
	v_cvt_f32_ubyte0_e32 v156, v152
	v_rcp_f32_e32 v151, v1
	v_pk_add_f32 v[156:157], v[156:157], 0.5 op_sel_hi:[1,0]
	v_cvt_f32_ubyte0_e32 v1, v155
	v_pk_mul_f32 v[146:147], v[156:157], v[146:147]
	v_add_f32_e32 v1, 0.5, v1
	v_pk_mul_f32 v[24:25], v[24:25], v[146:147]
	v_rcp_f32_e32 v146, v1
	v_cvt_f32_ubyte1_e32 v1, v155
	v_cvt_f32_ubyte3_e32 v159, v152
	v_cvt_f32_ubyte2_e32 v158, v152
	v_add_f32_e32 v1, 0.5, v1
	v_pk_add_f32 v[158:159], v[158:159], 0.5 op_sel_hi:[1,0]
	v_rcp_f32_e32 v147, v1
	v_cvt_f32_ubyte2_e32 v1, v155
	v_pk_mul_f32 v[150:151], v[158:159], v[150:151]
	v_add_f32_e32 v1, 0.5, v1
	v_pk_mul_f32 v[26:27], v[26:27], v[150:151]
	v_rcp_f32_e32 v150, v1
	v_cvt_f32_ubyte3_e32 v1, v155
	v_add_f32_e32 v1, 0.5, v1
	v_cvt_f32_ubyte1_e32 v155, v153
	v_cvt_f32_ubyte0_e32 v154, v153
	v_rcp_f32_e32 v151, v1
	v_pk_add_f32 v[154:155], v[154:155], 0.5 op_sel_hi:[1,0]
	v_cvt_f32_ubyte0_e32 v1, v160
	v_pk_mul_f32 v[146:147], v[154:155], v[146:147]
	v_add_f32_e32 v1, 0.5, v1
	v_pk_mul_f32 v[20:21], v[20:21], v[146:147]
	v_rcp_f32_e32 v146, v1
	v_cvt_f32_ubyte1_e32 v1, v160
	v_cvt_f32_ubyte3_e32 v157, v153
	v_cvt_f32_ubyte2_e32 v156, v153
	v_add_f32_e32 v1, 0.5, v1
	v_pk_add_f32 v[152:153], v[156:157], 0.5 op_sel_hi:[1,0]
	v_rcp_f32_e32 v147, v1
	v_cvt_f32_ubyte2_e32 v1, v160
	v_pk_mul_f32 v[150:151], v[152:153], v[150:151]
	v_add_f32_e32 v1, 0.5, v1
	v_pk_mul_f32 v[22:23], v[22:23], v[150:151]
	v_rcp_f32_e32 v150, v1
	v_cvt_f32_ubyte3_e32 v1, v160
	v_add_f32_e32 v1, 0.5, v1
	v_cvt_f32_ubyte1_e32 v153, v148
	v_cvt_f32_ubyte0_e32 v152, v148
	v_rcp_f32_e32 v151, v1
	v_pk_add_f32 v[152:153], v[152:153], 0.5 op_sel_hi:[1,0]
	v_cvt_f32_ubyte0_e32 v1, v161
	v_pk_mul_f32 v[146:147], v[152:153], v[146:147]
	v_add_f32_e32 v1, 0.5, v1
	v_pk_mul_f32 v[16:17], v[16:17], v[146:147]
	v_rcp_f32_e32 v146, v1
	v_cvt_f32_ubyte1_e32 v1, v161
	v_cvt_f32_ubyte3_e32 v155, v148
	v_cvt_f32_ubyte2_e32 v154, v148
	v_add_f32_e32 v1, 0.5, v1
	v_pk_add_f32 v[154:155], v[154:155], 0.5 op_sel_hi:[1,0]
	v_rcp_f32_e32 v147, v1
	v_cvt_f32_ubyte2_e32 v1, v161
	v_pk_mul_f32 v[150:151], v[154:155], v[150:151]
	v_add_f32_e32 v1, 0.5, v1
	v_pk_mul_f32 v[18:19], v[18:19], v[150:151]
	v_rcp_f32_e32 v150, v1
	v_cvt_f32_ubyte3_e32 v1, v161
	v_add_f32_e32 v1, 0.5, v1
	v_cvt_f32_ubyte1_e32 v153, v149
	v_cvt_f32_ubyte0_e32 v152, v149
	v_rcp_f32_e32 v151, v1
	v_pk_add_f32 v[152:153], v[152:153], 0.5 op_sel_hi:[1,0]
	v_cvt_f32_ubyte0_e32 v1, v144
	v_pk_mul_f32 v[146:147], v[152:153], v[146:147]
	v_add_f32_e32 v1, 0.5, v1
	v_pk_mul_f32 v[12:13], v[12:13], v[146:147]
	v_rcp_f32_e32 v146, v1
	v_cvt_f32_ubyte1_e32 v1, v144
	v_cvt_f32_ubyte3_e32 v155, v149
	v_cvt_f32_ubyte2_e32 v154, v149
	v_add_f32_e32 v1, 0.5, v1
	v_pk_add_f32 v[148:149], v[154:155], 0.5 op_sel_hi:[1,0]
	v_rcp_f32_e32 v147, v1
	v_cvt_f32_ubyte2_e32 v1, v144
	v_pk_mul_f32 v[148:149], v[148:149], v[150:151]
	v_add_f32_e32 v1, 0.5, v1
	v_pk_mul_f32 v[14:15], v[14:15], v[148:149]
	v_rcp_f32_e32 v148, v1
	v_cvt_f32_ubyte3_e32 v1, v144
	v_add_f32_e32 v1, 0.5, v1
	v_cvt_f32_ubyte1_e32 v151, v2
	v_cvt_f32_ubyte0_e32 v150, v2
	v_rcp_f32_e32 v149, v1
	v_pk_add_f32 v[150:151], v[150:151], 0.5 op_sel_hi:[1,0]
	v_cvt_f32_ubyte0_e32 v1, v145
	v_pk_mul_f32 v[146:147], v[150:151], v[146:147]
	v_add_f32_e32 v1, 0.5, v1
	v_pk_mul_f32 v[8:9], v[8:9], v[146:147]
	v_rcp_f32_e32 v146, v1
	v_cvt_f32_ubyte1_e32 v1, v145
	v_add_f32_e32 v1, 0.5, v1
	v_rcp_f32_e32 v147, v1
	v_cvt_f32_ubyte2_e32 v1, v145
	v_add_f32_e32 v1, 0.5, v1
	v_rcp_f32_e32 v144, v1
	v_cvt_f32_ubyte3_e32 v1, v145
	v_cvt_f32_ubyte3_e32 v153, v2
	v_cvt_f32_ubyte2_e32 v152, v2
	v_add_f32_e32 v1, 0.5, v1
	v_pk_add_f32 v[152:153], v[152:153], 0.5 op_sel_hi:[1,0]
	v_rcp_f32_e32 v145, v1
	v_pk_mul_f32 v[148:149], v[152:153], v[148:149]
	v_cvt_f32_ubyte3_e32 v151, v3
	v_pk_mul_f32 v[10:11], v[10:11], v[148:149]
	v_cvt_f32_ubyte1_e32 v149, v3
	v_cvt_f32_ubyte0_e32 v148, v3
	v_cvt_f32_ubyte2_e32 v150, v3
	v_pk_add_f32 v[2:3], v[150:151], 0.5 op_sel_hi:[1,0]
	v_pk_add_f32 v[148:149], v[148:149], 0.5 op_sel_hi:[1,0]
	v_pk_mul_f32 v[2:3], v[2:3], v[144:145]
	v_pk_mul_f32 v[146:147], v[148:149], v[146:147]
	v_pk_mul_f32 v[6:7], v[6:7], v[2:3]
	v_pk_mul_f32 v[4:5], v[4:5], v[146:147]
	s_branch .LBB0_44
